# compact proj epilogues (sigmoid, silu, plain+halo); tail round remapped to half-empty sample tiles with their pad-row MFMAs skipped; no tile-head vmcnt0
# speedup vs baseline: 1.0127x; 1.0023x over previous
;     __device__ bool next(int i, Unit& u) const {
;         const long L = (long)i * G + c; if (L >= nwg) return false;
;         int wgid = (int)L; { const int q = nwg / NXCD, r = nwg % NXCD, xcd = wgid % NXCD, off = wgid / NXCD; wgid = (xcd < r ? xcd * (q + 1) : r * (q + 1) + (xcd - r) * q) + off; }
;         const int nig = WGM * nN, gid = wgid / nig, fm = gid * WGM, gsz = (nM - fm) < WGM ? (nM - fm) : WGM;
;         u.pm = fm + ((wgid % nig) % gsz); u.pn = (wgid % nig) / gsz; return true;
.LBB0_689:
	v_readlane_b32 s1, v254, 47
	s_lshr_b32 s28, s1, 8
	s_mul_i32 s74, s0, s28
	v_writelane_b32 v255, s74, 8
	s_cmp_eq_u32 s28, 0x81
	s_cbranch_scc0 .Lrm_skip
	s_movk_i32 s28, 0x80
	s_lshl_b32 s74, s0, 7
.Lrm_skip:
	v_readlane_b32 s1, v253, 0
	s_cmp_lt_i32 s1, s74
	s_cselect_b64 s[2:3], -1, 0
	s_and_b64 vcc, exec, s[2:3]
	s_mul_i32 s29, s0, 7
	s_cbranch_vccz .LBB0_695
	s_lshr_b32 s6, s74, 3
	s_and_b32 s7, s74, 7
	s_add_i32 s5, s6, 1
	v_readlane_b32 s0, v253, 42
	s_cmp_ge_i32 s0, s7
	s_mov_b64 s[0:1], -1
	s_cbranch_scc0 .LBB0_692
	v_readlane_b32 s1, v253, 42
	s_sub_i32 s1, s1, s7
	s_mul_i32 s0, s5, s7
	s_mul_i32 s1, s1, s6
	s_add_i32 s4, s1, s0
	s_mov_b64 s[0:1], 0

;     __device__ bool next(int i, Unit& u) const {
;         const long L = (long)i * G + c; if (L >= nwg) return false;
;         int wgid = (int)L; { const int q = nwg / NXCD, r = nwg % NXCD, xcd = wgid % NXCD, off = wgid / NXCD; wgid = (xcd < r ? xcd * (q + 1) : r * (q + 1) + (xcd - r) * q) + off; }
;         const int nig = WGM * nN, gid = wgid / nig, fm = gid * WGM, gsz = (nM - fm) < WGM ? (nM - fm) : WGM;
;         u.pm = fm + ((wgid % nig) % gsz); u.pn = (wgid % nig) / gsz; return true;
.LBB0_702:
	s_add_i32 s60, s60, 1
	v_readlane_b32 s0, v253, 43
	v_readlane_b32 s2, v253, 1
	s_mul_i32 s0, s60, s0
	s_mul_hi_u32 s1, s60, s2
	s_add_i32 s1, s1, s0
	s_mul_i32 s0, s60, s2
	v_readlane_b32 s2, v253, 0
	s_add_u32 s0, s0, s2
	v_readlane_b32 s2, v253, 40
	s_addc_u32 s1, s1, s2
	v_readlane_b32 s100, v255, 8
	s_mov_b32 s101, 0
	s_nop 1
	v_mov_b64_e32 v[0:1], s[100:101]
	v_cmp_ge_i64_e64 s[42:43], s[0:1], v[0:1]
	v_cmp_lt_i64_e64 s[2:3], s[0:1], v[0:1]
	s_and_b64 vcc, exec, s[42:43]
	s_cbranch_vccnz .LBB0_708
	s_cmp_ge_u32 s0, s74
	s_cbranch_scc0 .Lrm_norm
	s_sub_i32 s12, s0, s74
	s_movk_i32 s89, 0x80
	s_branch .LBB0_708
.Lrm_norm:
	s_ashr_i32 s1, s0, 31
	s_lshr_b32 s1, s1, 29
	s_add_i32 s4, s0, s1
	s_and_b32 s1, s4, -8
	s_sub_i32 s5, s0, s1
	s_cmp_ge_i32 s5, s27
	s_mov_b64 s[0:1], -1
	s_cbranch_scc0 .LBB0_705
	s_sub_i32 s0, s5, s27
	v_readlane_b32 s1, v254, 60
	s_mul_i32 s0, s0, s1
	v_readlane_b32 s1, v254, 54
	s_mul_i32 s1, s1, s27
	s_add_i32 s10, s0, s1
	s_mov_b64 s[0:1], 0

; #define PG8_STAGE(bufoff, gbase, voff) do { _Pragma("unroll") for (int _i = 0; _i < 2; ++_i) \
;         __builtin_amdgcn_global_load_lds((const unsigned*)((const char*)(gbase) + (voff)[_i]), (LAS unsigned*)(lds + (bufoff) + ldsw + _i * 8192), 16, 0, 0); } while (0)
; #define PG8_LDA(dst, b, h) do { _Pragma("unroll") for (int m = 0; m < 4; ++m) _Pragma("unroll") for (int k = 0; k < 2; ++k) dst[m][k] = *(const LAS bf16x8*)(lds + PG8_SA(b, h) + aoff + m * 2048 + k * 1024); } while (0)
; #define PG8_LDB(dst, b, h) do { _Pragma("unroll") for (int n = 0; n < 2; ++n) _Pragma("unroll") for (int k = 0; k < 2; ++k) dst[n][k] = *(const LAS bf16x8*)(lds + PG8_SB(b, h) + boff + n * 2048 + k * 1024); } while (0)
; #define PG8_MMA(ai, bj, At, Bt) do { __builtin_amdgcn_s_setprio(1); _Pragma("unroll") for (int m = 0; m < 4; ++m) _Pragma("unroll") for (int n = 0; n < 2; ++n) _Pragma("unroll") for (int k = 0; k < 2; ++k) \
;         acc[ai][bj][m][n] = __builtin_amdgcn_mfma_f32_16x16x32_bf16(Bt[n][k], At[m][k], acc[ai][bj][m][n], 0, 0, 0); __builtin_amdgcn_s_setprio(0); } while (0)
; #define PG8_WAIT_V(n) asm volatile("s_waitcnt vmcnt(" #n ")" ::: "memory")
; #define PG8_WAIT_L(n) asm volatile("s_waitcnt lgkmcnt(" #n ")" ::: "memory")
; template <class Epi>
; __device__ __forceinline__ void gemm_phase(LAS unsigned char* lds, const Gemm g, const StaticOrder& S, const Epi& E, const int tidx) {
;     ...
;         for (int t = 0; t < nt; t += 2) {
;             const bool last = (t == nt - 2);
;             const char* a1 = cA + (size_t)(t + 1) * kstep;
;             const char* a2 = last ? nA : cA + (size_t)(t + 2) * kstep; const char* b2 = last ? nB : cB + (size_t)(t + 2) * kstep;
;             const char* a3 = a2 + kstep; const char* b3 = b2 + kstep;
;             PG8_LDB(B0, 0, 0); PG8_SCHED; PG8_LDA(At, 0, 0); PG8_STAGE(PG8_SA(1, 1), a1 + hstep, voffA);
;             PG8_WAIT_L(8); PG8_BAR; PG8_WAIT_L(0); PG8_MMA(0, 0, At, B0); PG8_BAR; PG8_SCHED;
;             PG8_LDB(B1, 0, 1); PG8_STAGE(PG8_SB(0, 0), b2, voffB);
;             PG8_BAR; PG8_WAIT_L(0); PG8_MMA(0, 1, At, B1); PG8_BAR;
;             PG8_LDA(At, 0, 1); PG8_STAGE(PG8_SA(0, 0), a2, voffA);
;             PG8_BAR; PG8_WAIT_L(0); PG8_MMA(1, 0, At, B0); PG8_BAR; PG8_SCHED;
;             PG8_STAGE(PG8_SB(0, 1), b2 + hstep, voffB);
;             PG8_WAIT_V(6); PG8_BAR; PG8_MMA(1, 1, At, B1); PG8_BAR;
.LBB0_713:
	s_add_i32 s8, s4, 2
	s_add_u32 s6, s2, 0x80
	s_addc_u32 s5, s3, 0
	s_add_i32 s9, 0, 0x10000
	v_add_u32_e32 v140, s9, v243
	s_waitcnt lgkmcnt(0)
	ds_read_b128 v[128:131], v140
	ds_read_b128 v[132:135], v140 offset:1024
	ds_read_b128 v[136:139], v140 offset:2048
	ds_read_b128 v[140:143], v140 offset:3072
	s_cmp_eq_u32 s59, s4
	s_cselect_b32 s4, s90, s6
	s_cselect_b32 s5, s91, s5
	s_cselect_b32 s7, s93, s1
	s_cselect_b32 s6, s92, s0
	v_lshl_add_u64 v[176:177], s[2:3], 0, v[206:207]
	s_add_i32 m0, s31, 0xc000
	ds_read_b128 v[144:147], v240
	ds_read_b128 v[148:151], v240 offset:1024
	ds_read_b128 v[152:155], v240 offset:2048
	ds_read_b128 v[156:159], v240 offset:3072
	ds_read_b128 v[160:163], v240 offset:4096
	ds_read_b128 v[164:167], v240 offset:5120
	ds_read_b128 v[168:171], v240 offset:6144
	ds_read_b128 v[172:175], v240 offset:7168
	global_load_lds_dwordx4 v[176:177], off
	v_lshl_add_u64 v[176:177], s[2:3], 0, v[208:209]
	s_add_i32 m0, s31, 0xe000
	s_nop 0
	global_load_lds_dwordx4 v[176:177], off
	s_waitcnt lgkmcnt(8)
	s_barrier
	s_waitcnt lgkmcnt(0)
	s_setprio 1
	s_waitcnt lgkmcnt(0)
	v_mfma_f32_16x16x32_bf16 v[116:119], v[128:131], v[144:147], v[116:119]
	v_mfma_f32_16x16x32_bf16 v[112:115], v[136:139], v[144:147], v[112:115]
	v_mfma_f32_16x16x32_bf16 v[100:103], v[128:131], v[152:155], v[100:103]
	v_mfma_f32_16x16x32_bf16 v[96:99], v[136:139], v[152:155], v[96:99]
	v_mfma_f32_16x16x32_bf16 v[84:87], v[128:131], v[160:163], v[84:87]
	v_mfma_f32_16x16x32_bf16 v[80:83], v[136:139], v[160:163], v[80:83]
	v_mfma_f32_16x16x32_bf16 v[68:71], v[128:131], v[168:171], v[68:71]
	v_mfma_f32_16x16x32_bf16 v[64:67], v[136:139], v[168:171], v[64:67]
	v_mfma_f32_16x16x32_bf16 v[116:119], v[132:135], v[148:151], v[116:119]
	v_mfma_f32_16x16x32_bf16 v[112:115], v[140:143], v[148:151], v[112:115]
	v_mfma_f32_16x16x32_bf16 v[100:103], v[132:135], v[156:159], v[100:103]
	v_mfma_f32_16x16x32_bf16 v[96:99], v[140:143], v[156:159], v[96:99]
	v_mfma_f32_16x16x32_bf16 v[84:87], v[132:135], v[164:167], v[84:87]
	v_mfma_f32_16x16x32_bf16 v[80:83], v[140:143], v[164:167], v[80:83]
	v_mfma_f32_16x16x32_bf16 v[68:71], v[132:135], v[172:175], v[68:71]
	v_mfma_f32_16x16x32_bf16 v[64:67], v[140:143], v[172:175], v[64:67]
	s_setprio 0
	s_barrier
	s_add_i32 s10, 0, 0x14000
	s_add_i32 s9, s9, s30
	v_add_u32_e32 v188, s10, v243
	v_lshl_add_u64 v[212:213], s[6:7], 0, v[202:203]
	s_mov_b32 m0, s9
	ds_read_b128 v[176:179], v188
	ds_read_b128 v[180:183], v188 offset:1024
	ds_read_b128 v[184:187], v188 offset:2048
	ds_read_b128 v[188:191], v188 offset:3072
	global_load_lds_dwordx4 v[212:213], off
	v_lshl_add_u64 v[214:215], s[6:7], 0, v[198:199]
	s_add_i32 m0, s9, 0x2000
	s_nop 0
	global_load_lds_dwordx4 v[214:215], off
	s_barrier
	s_waitcnt lgkmcnt(0)
	s_setprio 1
	s_waitcnt lgkmcnt(0)
	v_mfma_f32_16x16x32_bf16 v[124:127], v[176:179], v[144:147], v[124:127]
	v_mfma_f32_16x16x32_bf16 v[120:123], v[184:187], v[144:147], v[120:123]
	v_mfma_f32_16x16x32_bf16 v[108:111], v[176:179], v[152:155], v[108:111]
	v_mfma_f32_16x16x32_bf16 v[104:107], v[184:187], v[152:155], v[104:107]
	v_mfma_f32_16x16x32_bf16 v[92:95], v[176:179], v[160:163], v[92:95]
	v_mfma_f32_16x16x32_bf16 v[88:91], v[184:187], v[160:163], v[88:91]
	v_mfma_f32_16x16x32_bf16 v[76:79], v[176:179], v[168:171], v[76:79]
	v_mfma_f32_16x16x32_bf16 v[72:75], v[184:187], v[168:171], v[72:75]
	v_mfma_f32_16x16x32_bf16 v[124:127], v[180:183], v[148:151], v[124:127]
	v_mfma_f32_16x16x32_bf16 v[120:123], v[188:191], v[148:151], v[120:123]
	v_mfma_f32_16x16x32_bf16 v[108:111], v[180:183], v[156:159], v[108:111]
	v_mfma_f32_16x16x32_bf16 v[104:107], v[188:191], v[156:159], v[104:107]
	v_mfma_f32_16x16x32_bf16 v[92:95], v[180:183], v[164:167], v[92:95]
	v_mfma_f32_16x16x32_bf16 v[88:91], v[188:191], v[164:167], v[88:91]
	v_mfma_f32_16x16x32_bf16 v[76:79], v[180:183], v[172:175], v[76:79]
	v_mfma_f32_16x16x32_bf16 v[72:75], v[188:191], v[172:175], v[72:75]
	s_setprio 0
	s_mov_b32 m0, s31
	v_lshl_add_u64 v[216:217], s[4:5], 0, v[200:201]
	s_barrier
	ds_read_b128 v[144:147], v240 offset:16384
	ds_read_b128 v[148:151], v240 offset:17408
	ds_read_b128 v[152:155], v240 offset:18432
	ds_read_b128 v[156:159], v240 offset:19456
	ds_read_b128 v[160:163], v240 offset:20480
	ds_read_b128 v[164:167], v240 offset:21504
	ds_read_b128 v[168:171], v240 offset:22528
	ds_read_b128 v[172:175], v240 offset:23552
	global_load_lds_dwordx4 v[216:217], off
	v_lshl_add_u64 v[218:219], s[4:5], 0, v[196:197]
	s_mov_b32 m0, s34
	s_nop 0
	global_load_lds_dwordx4 v[218:219], off
	s_barrier
	s_waitcnt lgkmcnt(0)
	s_setprio 1
	s_waitcnt lgkmcnt(0)
	s_cmp_eq_u32 s13, 0x80
	s_cbranch_scc1 .Lskip_mma_2
	v_mfma_f32_16x16x32_bf16 v[52:55], v[128:131], v[144:147], v[52:55]
	v_mfma_f32_16x16x32_bf16 v[48:51], v[136:139], v[144:147], v[48:51]
	v_mfma_f32_16x16x32_bf16 v[36:39], v[128:131], v[152:155], v[36:39]
	v_mfma_f32_16x16x32_bf16 v[32:35], v[136:139], v[152:155], v[32:35]
	v_mfma_f32_16x16x32_bf16 v[20:23], v[128:131], v[160:163], v[20:23]
	v_mfma_f32_16x16x32_bf16 v[16:19], v[136:139], v[160:163], v[16:19]
	v_mfma_f32_16x16x32_bf16 v[4:7], v[128:131], v[168:171], v[4:7]
	v_mfma_f32_16x16x32_bf16 v[0:3], v[136:139], v[168:171], v[0:3]
	v_mfma_f32_16x16x32_bf16 v[52:55], v[132:135], v[148:151], v[52:55]
	v_mfma_f32_16x16x32_bf16 v[48:51], v[140:143], v[148:151], v[48:51]
	v_mfma_f32_16x16x32_bf16 v[36:39], v[132:135], v[156:159], v[36:39]
	v_mfma_f32_16x16x32_bf16 v[32:35], v[140:143], v[156:159], v[32:35]
	v_mfma_f32_16x16x32_bf16 v[20:23], v[132:135], v[164:167], v[20:23]
	v_mfma_f32_16x16x32_bf16 v[16:19], v[140:143], v[164:167], v[16:19]
	v_mfma_f32_16x16x32_bf16 v[4:7], v[132:135], v[172:175], v[4:7]
	v_mfma_f32_16x16x32_bf16 v[0:3], v[140:143], v[172:175], v[0:3]
; #define PG8_STAGE(bufoff, gbase, voff) do { _Pragma("unroll") for (int _i = 0; _i < 2; ++_i) \
;         __builtin_amdgcn_global_load_lds((const unsigned*)((const char*)(gbase) + (voff)[_i]), (LAS unsigned*)(lds + (bufoff) + ldsw + _i * 8192), 16, 0, 0); } while (0)
; #define PG8_LDA(dst, b, h) do { _Pragma("unroll") for (int m = 0; m < 4; ++m) _Pragma("unroll") for (int k = 0; k < 2; ++k) dst[m][k] = *(const LAS bf16x8*)(lds + PG8_SA(b, h) + aoff + m * 2048 + k * 1024); } while (0)
; #define PG8_LDB(dst, b, h) do { _Pragma("unroll") for (int n = 0; n < 2; ++n) _Pragma("unroll") for (int k = 0; k < 2; ++k) dst[n][k] = *(const LAS bf16x8*)(lds + PG8_SB(b, h) + boff + n * 2048 + k * 1024); } while (0)
; #define PG8_MMA(ai, bj, At, Bt) do { __builtin_amdgcn_s_setprio(1); _Pragma("unroll") for (int m = 0; m < 4; ++m) _Pragma("unroll") for (int n = 0; n < 2; ++n) _Pragma("unroll") for (int k = 0; k < 2; ++k) \
;         acc[ai][bj][m][n] = __builtin_amdgcn_mfma_f32_16x16x32_bf16(Bt[n][k], At[m][k], acc[ai][bj][m][n], 0, 0, 0); __builtin_amdgcn_s_setprio(0); } while (0)
; #define PG8_WAIT_V(n) asm volatile("s_waitcnt vmcnt(" #n ")" ::: "memory")
; #define PG8_WAIT_L(n) asm volatile("s_waitcnt lgkmcnt(" #n ")" ::: "memory")
; #define PG8_BAR __builtin_amdgcn_s_barrier()
; #define PG8_SCHED __builtin_amdgcn_sched_barrier(0)
; template <class Epi>
; __device__ __forceinline__ void gemm_phase(LAS unsigned char* lds, const Gemm g, const StaticOrder& S, const Epi& E, const int tidx) {
;     ...
;             PG8_BAR; PG8_WAIT_L(0); PG8_MMA(1, 0, At, B0); PG8_BAR; PG8_SCHED;
;             PG8_STAGE(PG8_SB(0, 1), b2 + hstep, voffB);
;             PG8_WAIT_V(6); PG8_BAR; PG8_MMA(1, 1, At, B1); PG8_BAR;
;             PG8_LDB(B0, 1, 0); PG8_SCHED; PG8_LDA(At, 1, 0); PG8_STAGE(PG8_SA(0, 1), a2 + hstep, voffA);
;             PG8_WAIT_L(8); PG8_BAR; PG8_WAIT_L(0); PG8_MMA(0, 0, At, B0); PG8_BAR; PG8_SCHED;
;             PG8_LDB(B1, 1, 1); PG8_STAGE(PG8_SB(1, 0), b3, voffB);
;             PG8_BAR; PG8_WAIT_L(0); PG8_MMA(0, 1, At, B1); PG8_BAR;
;             PG8_LDA(At, 1, 1); PG8_STAGE(PG8_SA(1, 0), a3, voffA);
;             PG8_BAR; PG8_WAIT_L(0); PG8_MMA(1, 0, At, B0); PG8_BAR; PG8_SCHED;
.Lskip_mma_2:
	s_setprio 0
	s_barrier
	s_add_u32 s6, s6, s14
	s_addc_u32 s7, s7, 0
	s_add_i32 s9, s10, s30
	v_lshl_add_u64 v[220:221], s[6:7], 0, v[202:203]
	s_mov_b32 m0, s9
	v_lshl_add_u64 v[222:223], s[6:7], 0, v[198:199]
	global_load_lds_dwordx4 v[220:221], off
	s_add_i32 m0, s9, 0x2000
	s_nop 0
	global_load_lds_dwordx4 v[222:223], off
	s_waitcnt vmcnt(6)
	s_barrier
	s_setprio 1
	s_cmp_eq_u32 s13, 0x80
	s_cbranch_scc1 .Lskip_mma_3
	v_mfma_f32_16x16x32_bf16 v[60:63], v[176:179], v[144:147], v[60:63]
	v_mfma_f32_16x16x32_bf16 v[56:59], v[184:187], v[144:147], v[56:59]
	v_mfma_f32_16x16x32_bf16 v[44:47], v[176:179], v[152:155], v[44:47]
	v_mfma_f32_16x16x32_bf16 v[40:43], v[184:187], v[152:155], v[40:43]
	v_mfma_f32_16x16x32_bf16 v[28:31], v[176:179], v[160:163], v[28:31]
	v_mfma_f32_16x16x32_bf16 v[24:27], v[184:187], v[160:163], v[24:27]
	v_mfma_f32_16x16x32_bf16 v[12:15], v[176:179], v[168:171], v[12:15]
	v_mfma_f32_16x16x32_bf16 v[8:11], v[184:187], v[168:171], v[8:11]
	v_mfma_f32_16x16x32_bf16 v[60:63], v[180:183], v[148:151], v[60:63]
	v_mfma_f32_16x16x32_bf16 v[56:59], v[188:191], v[148:151], v[56:59]
	v_mfma_f32_16x16x32_bf16 v[44:47], v[180:183], v[156:159], v[44:47]
	v_mfma_f32_16x16x32_bf16 v[40:43], v[188:191], v[156:159], v[40:43]
	v_mfma_f32_16x16x32_bf16 v[28:31], v[180:183], v[164:167], v[28:31]
	v_mfma_f32_16x16x32_bf16 v[24:27], v[188:191], v[164:167], v[24:27]
	v_mfma_f32_16x16x32_bf16 v[12:15], v[180:183], v[172:175], v[12:15]
	v_mfma_f32_16x16x32_bf16 v[8:11], v[188:191], v[172:175], v[8:11]
.Lskip_mma_3:
	s_setprio 0
	s_add_i32 s6, 0, 0x18000
	v_add_u32_e32 v140, s6, v243
	s_barrier
	ds_read_b128 v[128:131], v140
	ds_read_b128 v[132:135], v140 offset:1024
	ds_read_b128 v[136:139], v140 offset:2048
	ds_read_b128 v[140:143], v140 offset:3072
	s_add_u32 s4, s4, s14
	s_addc_u32 s5, s5, 0
	s_mov_b32 m0, s35
	v_lshl_add_u64 v[176:177], s[4:5], 0, v[200:201]
	ds_read_b128 v[144:147], v240 offset:32768
	ds_read_b128 v[148:151], v240 offset:33792
	ds_read_b128 v[152:155], v240 offset:34816
	ds_read_b128 v[156:159], v240 offset:35840
	ds_read_b128 v[160:163], v240 offset:36864
	ds_read_b128 v[164:167], v240 offset:37888
	ds_read_b128 v[168:171], v240 offset:38912
	ds_read_b128 v[172:175], v240 offset:39936
	global_load_lds_dwordx4 v[176:177], off
	v_lshl_add_u64 v[176:177], s[4:5], 0, v[196:197]
	s_mov_b32 m0, s54
	s_nop 0
	global_load_lds_dwordx4 v[176:177], off
	s_waitcnt lgkmcnt(8)
	s_barrier
	s_waitcnt lgkmcnt(0)
	s_setprio 1
	s_waitcnt lgkmcnt(0)
	v_mfma_f32_16x16x32_bf16 v[116:119], v[128:131], v[144:147], v[116:119]
	v_mfma_f32_16x16x32_bf16 v[112:115], v[136:139], v[144:147], v[112:115]
	v_mfma_f32_16x16x32_bf16 v[100:103], v[128:131], v[152:155], v[100:103]
	v_mfma_f32_16x16x32_bf16 v[96:99], v[136:139], v[152:155], v[96:99]
	v_mfma_f32_16x16x32_bf16 v[84:87], v[128:131], v[160:163], v[84:87]
	v_mfma_f32_16x16x32_bf16 v[80:83], v[136:139], v[160:163], v[80:83]
	v_mfma_f32_16x16x32_bf16 v[68:71], v[128:131], v[168:171], v[68:71]
	v_mfma_f32_16x16x32_bf16 v[64:67], v[136:139], v[168:171], v[64:67]
	v_mfma_f32_16x16x32_bf16 v[116:119], v[132:135], v[148:151], v[116:119]
	v_mfma_f32_16x16x32_bf16 v[112:115], v[140:143], v[148:151], v[112:115]
	v_mfma_f32_16x16x32_bf16 v[100:103], v[132:135], v[156:159], v[100:103]
	v_mfma_f32_16x16x32_bf16 v[96:99], v[140:143], v[156:159], v[96:99]
	v_mfma_f32_16x16x32_bf16 v[84:87], v[132:135], v[164:167], v[84:87]
	v_mfma_f32_16x16x32_bf16 v[80:83], v[140:143], v[164:167], v[80:83]
	v_mfma_f32_16x16x32_bf16 v[68:71], v[132:135], v[172:175], v[68:71]
	v_mfma_f32_16x16x32_bf16 v[64:67], v[140:143], v[172:175], v[64:67]
	s_setprio 0
	s_barrier
	s_add_i32 s4, 0, 0x1c000
	s_add_i32 s5, s6, s30
	v_add_u32_e32 v188, s4, v243
	v_lshl_add_u64 v[212:213], v[212:213], 0, s[16:17]
	s_mov_b32 m0, s5
	ds_read_b128 v[176:179], v188
	ds_read_b128 v[180:183], v188 offset:1024
	ds_read_b128 v[184:187], v188 offset:2048
	ds_read_b128 v[188:191], v188 offset:3072
	global_load_lds_dwordx4 v[212:213], off
	v_lshl_add_u64 v[212:213], v[214:215], 0, s[16:17]
	s_add_i32 m0, s5, 0x2000
	s_nop 0
	global_load_lds_dwordx4 v[212:213], off
	s_barrier
	s_waitcnt lgkmcnt(0)
	s_setprio 1
	s_waitcnt lgkmcnt(0)
	v_mfma_f32_16x16x32_bf16 v[124:127], v[176:179], v[144:147], v[124:127]
	v_mfma_f32_16x16x32_bf16 v[120:123], v[184:187], v[144:147], v[120:123]
	v_mfma_f32_16x16x32_bf16 v[108:111], v[176:179], v[152:155], v[108:111]
	v_mfma_f32_16x16x32_bf16 v[104:107], v[184:187], v[152:155], v[104:107]
	v_mfma_f32_16x16x32_bf16 v[92:95], v[176:179], v[160:163], v[92:95]
	v_mfma_f32_16x16x32_bf16 v[88:91], v[184:187], v[160:163], v[88:91]
	v_mfma_f32_16x16x32_bf16 v[76:79], v[176:179], v[168:171], v[76:79]
	v_mfma_f32_16x16x32_bf16 v[72:75], v[184:187], v[168:171], v[72:75]
	v_mfma_f32_16x16x32_bf16 v[124:127], v[180:183], v[148:151], v[124:127]
	v_mfma_f32_16x16x32_bf16 v[120:123], v[188:191], v[148:151], v[120:123]
	v_mfma_f32_16x16x32_bf16 v[108:111], v[180:183], v[156:159], v[108:111]
	v_mfma_f32_16x16x32_bf16 v[104:107], v[188:191], v[156:159], v[104:107]
	v_mfma_f32_16x16x32_bf16 v[92:95], v[180:183], v[164:167], v[92:95]
	v_mfma_f32_16x16x32_bf16 v[88:91], v[188:191], v[164:167], v[88:91]
	v_mfma_f32_16x16x32_bf16 v[76:79], v[180:183], v[172:175], v[76:79]
	v_mfma_f32_16x16x32_bf16 v[72:75], v[188:191], v[172:175], v[72:75]
	s_setprio 0
	s_mov_b32 m0, s57
	v_lshl_add_u64 v[212:213], v[216:217], 0, s[16:17]
	s_barrier
; #define INP(i) (*(const float* const __attribute__((address_space(4)))*)(ka_base() + 8 * (i)))
; #define OUTP() (*(float* const __attribute__((address_space(4)))*)(ka_base() + 8 * 21))
; #define WSP() (*(unsigned char* const __attribute__((address_space(4)))*)(ka_base() + 8 * 22))
; #define PG8_STAGE(bufoff, gbase, voff) do { _Pragma("unroll") for (int _i = 0; _i < 2; ++_i) \
;         __builtin_amdgcn_global_load_lds((const unsigned*)((const char*)(gbase) + (voff)[_i]), (LAS unsigned*)(lds + (bufoff) + ldsw + _i * 8192), 16, 0, 0); } while (0)
; #define PG8_MMA(ai, bj, At, Bt) do { __builtin_amdgcn_s_setprio(1); _Pragma("unroll") for (int m = 0; m < 4; ++m) _Pragma("unroll") for (int n = 0; n < 2; ++n) _Pragma("unroll") for (int k = 0; k < 2; ++k) \
;         acc[ai][bj][m][n] = __builtin_amdgcn_mfma_f32_16x16x32_bf16(Bt[n][k], At[m][k], acc[ai][bj][m][n], 0, 0, 0); __builtin_amdgcn_s_setprio(0); } while (0)
; #define PG8_WAIT_V(n) asm volatile("s_waitcnt vmcnt(" #n ")" ::: "memory")
; #define PG8_WAIT_L(n) asm volatile("s_waitcnt lgkmcnt(" #n ")" ::: "memory")
; #define PG8_BAR __builtin_amdgcn_s_barrier()
; template <class Epi>
; __device__ __forceinline__ void gemm_phase(LAS unsigned char* lds, const Gemm g, const StaticOrder& S, const Epi& E, const int tidx) {
;     ...
;             PG8_BAR; PG8_WAIT_L(0); PG8_MMA(1, 0, At, B0); PG8_BAR; PG8_SCHED;
;             PG8_STAGE(PG8_SB(1, 1), b3 + hstep, voffB);
;             PG8_WAIT_V(6); PG8_BAR; PG8_MMA(1, 1, At, B1); PG8_BAR;
;         }
;         E(acc, cur, wr, wc, fr, fq);
;         if (!has_next) break;
;     __device__ __forceinline__ void res(const f32x4 (&acc)[2][2][4][2], const pg8::Unit& u, int wr, int wc, int fr, int fq) const {
;         float* out = OUTP(); bf16_t* xb = (bf16_t*)(WSP() + WS_XB);
;         const int row0 = u.pm * 256 + wr * 64 + fr, col0 = u.pn * 256 + wc * 32 + 4 * fq;
; #pragma unroll
;         for (int ai = 0; ai < 2; ++ai) {
;             f32x4 xin[4][2][2];
; #pragma unroll
;             for (int m = 0; m < 4; ++m) {
;                 const int r = row0 + ai * 128 + m * 16;
;                 const bool ok = row_valid(g, r);
;                 const int rq = ok ? r : 0;
;                 const float* yp = (first ? (rq < 32768 ? INP(0) + ((size_t)g * 32768 + rq) * 1024 : INP(1) + (size_t)(rq - 32768) * 1024) : (const float*)yrow(out, g, rq)) + col0;
	ds_read_b128 v[144:147], v240 offset:49152
	ds_read_b128 v[148:151], v240 offset:50176
	ds_read_b128 v[152:155], v240 offset:51200
	ds_read_b128 v[156:159], v240 offset:52224
	ds_read_b128 v[160:163], v240 offset:53248
	ds_read_b128 v[164:167], v240 offset:54272
	ds_read_b128 v[168:171], v240 offset:55296
	ds_read_b128 v[172:175], v240 offset:56320
	global_load_lds_dwordx4 v[212:213], off
	v_lshl_add_u64 v[212:213], v[218:219], 0, s[16:17]
	s_mov_b32 m0, s58
	s_nop 0
	global_load_lds_dwordx4 v[212:213], off
	s_barrier
	s_waitcnt lgkmcnt(0)
	s_setprio 1
	s_waitcnt lgkmcnt(0)
	s_cmp_eq_u32 s13, 0x80
	s_cbranch_scc1 .Lskip_mma_6
	v_mfma_f32_16x16x32_bf16 v[52:55], v[128:131], v[144:147], v[52:55]
	v_mfma_f32_16x16x32_bf16 v[48:51], v[136:139], v[144:147], v[48:51]
	v_mfma_f32_16x16x32_bf16 v[36:39], v[128:131], v[152:155], v[36:39]
	v_mfma_f32_16x16x32_bf16 v[32:35], v[136:139], v[152:155], v[32:35]
	v_mfma_f32_16x16x32_bf16 v[20:23], v[128:131], v[160:163], v[20:23]
	v_mfma_f32_16x16x32_bf16 v[16:19], v[136:139], v[160:163], v[16:19]
	v_mfma_f32_16x16x32_bf16 v[4:7], v[128:131], v[168:171], v[4:7]
	v_mfma_f32_16x16x32_bf16 v[0:3], v[136:139], v[168:171], v[0:3]
	v_mfma_f32_16x16x32_bf16 v[52:55], v[132:135], v[148:151], v[52:55]
	v_mfma_f32_16x16x32_bf16 v[48:51], v[140:143], v[148:151], v[48:51]
	v_mfma_f32_16x16x32_bf16 v[36:39], v[132:135], v[156:159], v[36:39]
	v_mfma_f32_16x16x32_bf16 v[32:35], v[140:143], v[156:159], v[32:35]
	v_mfma_f32_16x16x32_bf16 v[20:23], v[132:135], v[164:167], v[20:23]
	v_mfma_f32_16x16x32_bf16 v[16:19], v[140:143], v[164:167], v[16:19]
	v_mfma_f32_16x16x32_bf16 v[4:7], v[132:135], v[172:175], v[4:7]
	v_mfma_f32_16x16x32_bf16 v[0:3], v[140:143], v[172:175], v[0:3]
.Lskip_mma_6:
	s_setprio 0
	s_barrier
	s_add_i32 s4, s4, s30
	v_lshl_add_u64 v[128:129], v[220:221], 0, s[16:17]
	s_mov_b32 m0, s4
	s_nop 0
	global_load_lds_dwordx4 v[128:129], off
	v_lshl_add_u64 v[128:129], v[222:223], 0, s[16:17]
	s_add_i32 m0, s4, 0x2000
	s_nop 0
	global_load_lds_dwordx4 v[128:129], off
	s_waitcnt vmcnt(6)
	s_barrier
	s_setprio 1
	s_cmp_eq_u32 s13, 0x80
	s_cbranch_scc1 .Lskip_mma_7
	v_mfma_f32_16x16x32_bf16 v[60:63], v[176:179], v[144:147], v[60:63]
	v_mfma_f32_16x16x32_bf16 v[56:59], v[184:187], v[144:147], v[56:59]
	v_mfma_f32_16x16x32_bf16 v[44:47], v[176:179], v[152:155], v[44:47]
	v_mfma_f32_16x16x32_bf16 v[40:43], v[184:187], v[152:155], v[40:43]
	v_mfma_f32_16x16x32_bf16 v[28:31], v[176:179], v[160:163], v[28:31]
	v_mfma_f32_16x16x32_bf16 v[24:27], v[184:187], v[160:163], v[24:27]
	v_mfma_f32_16x16x32_bf16 v[12:15], v[176:179], v[168:171], v[12:15]
	v_mfma_f32_16x16x32_bf16 v[8:11], v[184:187], v[168:171], v[8:11]
	v_mfma_f32_16x16x32_bf16 v[60:63], v[180:183], v[148:151], v[60:63]
	v_mfma_f32_16x16x32_bf16 v[56:59], v[188:191], v[148:151], v[56:59]
	v_mfma_f32_16x16x32_bf16 v[44:47], v[180:183], v[156:159], v[44:47]
	v_mfma_f32_16x16x32_bf16 v[40:43], v[188:191], v[156:159], v[40:43]
	v_mfma_f32_16x16x32_bf16 v[28:31], v[180:183], v[164:167], v[28:31]
	v_mfma_f32_16x16x32_bf16 v[24:27], v[188:191], v[164:167], v[24:27]
	v_mfma_f32_16x16x32_bf16 v[12:15], v[180:183], v[172:175], v[12:15]
	v_mfma_f32_16x16x32_bf16 v[8:11], v[188:191], v[172:175], v[8:11]
.Lskip_mma_7:
	s_setprio 0
	s_add_u32 s2, s2, 0x100
	s_addc_u32 s3, s3, 0
	s_add_u32 s0, s0, 0x100
	s_addc_u32 s1, s1, 0
	s_cmp_ge_u32 s8, s55
	s_mov_b32 s4, s8
	s_barrier
	s_cbranch_scc0 .LBB0_713
	s_mov_b64 s[0:1], -1
	s_mov_b64 s[94:95], 0
	s_cmp_lt_i32 s26, 3
	s_mov_b64 s[2:3], 0
	s_cbranch_scc1 .LBB0_789
	s_cmp_gt_i32 s26, 3
	s_cbranch_scc0 .LBB0_994
	s_cmp_eq_u32 s26, 4
	s_mov_b64 s[2:3], -1
	s_cbranch_scc0 .LBB0_993
	v_readlane_b32 s6, v254, 34
	v_readlane_b32 s7, v254, 35
	s_mov_b64 s[0:1], s[6:7]
	s_load_dwordx2 s[96:97], s[0:1], 0xa8
	v_lshl_add_u32 v214, s13, 8, v239
	v_readlane_b32 s0, v254, 39
	s_mov_b32 s10, 0x8000
	v_cmp_gt_i32_e32 vcc, s61, v214
	v_readlane_b32 s1, v254, 40
	v_cmp_gt_i32_e64 s[2:3], s10, v214
	s_and_b64 s[0:1], s[0:1], vcc
	s_or_b64 s[8:9], s[2:3], s[0:1]
	v_cndmask_b32_e64 v128, 0, v214, s[8:9]
	s_movk_i32 s0, 0x7fff
	v_add_u32_e32 v192, 0xffff8000, v128
	v_ashrrev_i32_e32 v129, 31, v128
	v_cmp_gt_i32_e64 s[44:45], s10, v128
	v_cmp_lt_i32_e64 s[4:5], s0, v128
	s_mov_b64 s[0:1], -1
	s_and_b64 vcc, exec, s[78:79]
	v_cndmask_b32_e64 v219, 0, v129, s[44:45]
	v_cndmask_b32_e64 v218, v192, v128, s[44:45]
	s_cbranch_vccz .LBB0_719
	v_mov_b32_e32 v130, s81
	v_cndmask_b32_e64 v130, v248, v130, s[44:45]
	v_mov_b32_e32 v131, v193
	s_waitcnt lgkmcnt(0)
	v_lshl_add_u64 v[132:133], s[96:97], 0, v[130:131]
	s_mov_b64 s[0:1], 0
	v_mov_b64_e32 v[130:131], v[218:219]

; __device__ __forceinline__ unsigned cvt_pk_bf16(float lo, float hi) { const f32x2 v = {lo, hi}; const bf16v2_t b = __builtin_convertvector(v, bf16v2_t); return __builtin_bit_cast(unsigned, b); }
; __device__ __forceinline__ float sigmoidf_(float x) { return __builtin_amdgcn_rcpf(1.0f + __builtin_amdgcn_exp2f(x * -1.44269504089f)); }
;     __device__ __forceinline__ void epi_proj(const f32x4 (&acc)[2][2][4][2], const pg8::Unit& u, int wr, int wc, int fr, int fq) const {
;     ...
;             for (int m = 0; m < 4; ++m) rstd8[ai][m] = rs[row0 + ai * 128 + m * 16];
; #pragma unroll
;         for (int ai = 0; ai < 2; ++ai)
; #pragma unroll
;             for (int m = 0; m < 4; ++m) rstd8[ai][m] = rsqrtf(rstd8[ai][m] * (1.0f / 1024.0f) + EPS);
;     ...
;                         const int slot = u.pn >> 2;
;                         bf16_t* rowp = act + (size_t)slot * SLOT_EL + (size_t)r * 1024 + (colt & 1023);
; #pragma unroll
;                         for (int bj = 0; bj < 2; ++bj) {
;                             f32x4 v0 = acc[ai][bj][m][0] * rstd, v1 = acc[ai][bj][m][1] * rstd;
;                             if (slot < 2) {
;                                 f32x2 a = gelu_pk((f32x2){v0[0], v0[1]}), b = gelu_pk((f32x2){v0[2], v0[3]}), c = gelu_pk((f32x2){v1[0], v1[1]}), d = gelu_pk((f32x2){v1[2], v1[3]});
;                                 v0 = (f32x4){a.x, a.y, b.x, b.y}; v1 = (f32x4){c.x, c.y, d.x, d.y};
;                             } else if (slot == 5) {
; #pragma unroll
;                                 for (int j = 0; j < 4; ++j) { v0[j] = siluf_(v0[j]); v1[j] = siluf_(v1[j]); }
;                             } else if (slot >= 6) {
; #pragma unroll
;                                 for (int j = 0; j < 4; ++j) { v0[j] = sigmoidf_(v0[j]); v1[j] = sigmoidf_(v1[j]); }
;                             }
;                             u32x4 w; w.x = cvt_pk_bf16(v0[0], v0[1]); w.y = cvt_pk_bf16(v0[2], v0[3]); w.z = cvt_pk_bf16(v1[0], v1[1]); w.w = cvt_pk_bf16(v1[2], v1[3]);
;                             *(u32x4*)(rowp + bj * 128) = w;
;                             if (slot >= 2 && slot <= 4) {
;                                 const int ch = (slot - 2) * 1024 + (colt & 1023) + bj * 128;
;                                 if ((r & 63) >= 61) *(u32x4*)(halo + ((size_t)(r >> 6) * 3 + ((r & 63) - 61)) * 3072 + ch) = w;
.Lepi_plain:
	v_readlane_b32 s6, v254, 34
	v_readlane_b32 s7, v254, 35
	s_mov_b64 s[0:1], s[6:7]
	s_load_dwordx2 s[4:5], s[0:1], 0xb0
	s_mov_b64 s[0:1], s[6:7]
	s_mov_b64 s[0:1], s[6:7]
	s_mov_b64 s[0:1], s[6:7]
	s_mov_b64 s[0:1], s[6:7]
	v_lshl_add_u32 v136, s13, 8, v239
	v_ashrrev_i32_e32 v137, 31, v136
	s_mov_b64 s[0:1], s[6:7]
	s_waitcnt lgkmcnt(0)
	v_lshl_add_u64 v[128:129], v[136:137], 2, s[66:67]
	global_load_dword v130, v[128:129], off
	global_load_dword v131, v[128:129], off offset:64
	global_load_dword v132, v[128:129], off offset:128
	global_load_dword v133, v[128:129], off offset:192
	global_load_dword v134, v[128:129], off offset:512
	global_load_dword v135, v[128:129], off offset:576
	global_load_dword v139, v[128:129], off offset:640
	s_nop 0
	global_load_dword v128, v[128:129], off offset:704
	s_mov_b32 s0, 0x800000
	v_lshl_or_b32 v152, s88, 8, v245
	v_and_b32_e32 v152, 0x3ff, v152
	v_ashrrev_i32_e32 v153, 31, v152
	v_lshl_add_u64 v[152:153], v[152:153], 1, s[4:5]
	v_or_b32_e32 v146, 16, v136
	v_or_b32_e32 v142, 32, v136
	v_or_b32_e32 v140, 48, v136
	v_lshlrev_b64 v[136:137], 11, v[136:137]
	v_ashrrev_i32_e32 v147, 31, v146
	v_lshlrev_b64 v[146:147], 11, v[146:147]
	v_ashrrev_i32_e32 v143, 31, v142
	v_lshlrev_b64 v[142:143], 11, v[142:143]
	v_ashrrev_i32_e32 v141, 31, v140
	v_lshlrev_b64 v[140:141], 11, v[140:141]
	s_waitcnt vmcnt(0)
	v_fmamk_f32 v129, v130, 0x3a800000, v237
	v_cmp_gt_f32_e32 vcc, s0, v129
	v_mul_f32_e32 v130, 0x4b800000, v129
	v_fmamk_f32 v128, v128, 0x3a800000, v237
	v_cndmask_b32_e32 v129, v129, v130, vcc
	v_rsq_f32_e32 v129, v129
	s_nop 0
	v_mul_f32_e32 v130, 0x45800000, v129
	v_cndmask_b32_e32 v150, v129, v130, vcc
	v_fmamk_f32 v129, v131, 0x3a800000, v237
	v_cmp_gt_f32_e32 vcc, s0, v129
	v_mul_f32_e32 v130, 0x4b800000, v129
	v_pk_mul_f32 v[154:155], v[118:119], v[150:151] op_sel_hi:[1,0]
	v_cndmask_b32_e32 v129, v129, v130, vcc
	v_rsq_f32_e32 v129, v129
	v_pk_mul_f32 v[156:157], v[116:117], v[150:151] op_sel_hi:[1,0]
	v_pk_mul_f32 v[158:159], v[114:115], v[150:151] op_sel_hi:[1,0]
	v_pk_mul_f32 v[160:161], v[112:113], v[150:151] op_sel_hi:[1,0]
	v_mul_f32_e32 v130, 0x45800000, v129
	v_cndmask_b32_e32 v148, v129, v130, vcc
	v_fmamk_f32 v129, v132, 0x3a800000, v237
	v_cmp_gt_f32_e32 vcc, s0, v129
	v_mul_f32_e32 v130, 0x4b800000, v129
	v_cndmask_b32_e32 v129, v129, v130, vcc
	v_rsq_f32_e32 v129, v129
	v_mul_f32_e32 v130, 0x45800000, v129
	v_cndmask_b32_e32 v144, v129, v130, vcc
	v_fmamk_f32 v129, v133, 0x3a800000, v237
	v_cmp_gt_f32_e32 vcc, s0, v129
	v_mul_f32_e32 v130, 0x4b800000, v129
	v_cndmask_b32_e32 v129, v129, v130, vcc
	v_rsq_f32_e32 v129, v129
	v_mul_f32_e32 v130, 0x45800000, v129
	v_cndmask_b32_e32 v138, v129, v130, vcc
	v_fmamk_f32 v129, v134, 0x3a800000, v237
	v_cmp_gt_f32_e32 vcc, s0, v129
	v_mul_f32_e32 v130, 0x4b800000, v129
	v_cndmask_b32_e32 v129, v129, v130, vcc
	v_rsq_f32_e32 v129, v129
	v_mov_b32_e32 v162, v154
	v_mov_b32_e32 v163, v155
	v_mul_f32_e32 v130, 0x45800000, v129
	v_cndmask_b32_e32 v134, v129, v130, vcc
	v_fmamk_f32 v129, v135, 0x3a800000, v237
	v_cmp_gt_f32_e32 vcc, s0, v129
	v_mul_f32_e32 v130, 0x4b800000, v129
	v_cvt_pk_bf16_f32 v154, v156, v157
	v_cndmask_b32_e32 v129, v129, v130, vcc
	v_rsq_f32_e32 v129, v129
	v_cvt_pk_bf16_f32 v155, v162, v163
	v_cvt_pk_bf16_f32 v156, v160, v161
	v_cvt_pk_bf16_f32 v157, v158, v159
	v_mul_f32_e32 v130, 0x45800000, v129
	v_cndmask_b32_e32 v132, v129, v130, vcc
	v_fmamk_f32 v129, v139, 0x3a800000, v237
	v_cmp_gt_f32_e32 vcc, s0, v129
	v_mul_f32_e32 v130, 0x4b800000, v129
	v_pk_mul_f32 v[158:159], v[122:123], v[150:151] op_sel_hi:[1,0]
	v_cndmask_b32_e32 v129, v129, v130, vcc
	v_rsq_f32_e32 v129, v129
	v_mul_f32_e32 v130, 0x45800000, v129
	v_cndmask_b32_e32 v130, v129, v130, vcc
	v_cmp_gt_f32_e32 vcc, s0, v128
	s_lshl_b32 s100, s13, 2
	s_lshr_b32 s101, s56, 6
	s_add_i32 s100, s100, s101
	s_mul_i32 s100, s100, 3
	v_add_u32_e32 v164, s100, v204
	s_movk_i32 s101, 0x1800
	v_mul_lo_u32 v164, v164, s101
	v_mov_b32_e32 v165, 0
	s_lshr_b32 s100, s88, 2
	s_sub_i32 s100, s100, 2
	s_lshl_b32 s100, s100, 11
	s_add_u32 s100, s100, 0x33400000
	s_mov_b32 s101, 0
	v_lshl_add_u64 v[166:167], v[152:153], 0, v[164:165]
	v_lshl_add_u64 v[166:167], v[166:167], 0, s[100:101]
	s_mov_b64 s[100:101], 0x9000
	v_lshl_add_u64 v[168:169], v[166:167], 0, s[100:101]
	s_lshr_b32 s0, s88, 2
	s_mul_i32 s0, s0, 0x4080000
	s_add_u32 s0, s0, 0x8d80000
	s_mov_b32 s1, 0
	v_lshl_add_u64 v[152:153], v[152:153], 0, s[0:1]
	v_lshl_add_u64 v[136:137], v[152:153], 0, v[136:137]
	global_store_dwordx4 v[136:137], v[154:157], off
	v_mul_f32_e32 v129, 0x4b800000, v128
	v_cndmask_b32_e32 v128, v128, v129, vcc
	v_pk_mul_f32 v[154:155], v[126:127], v[150:151] op_sel_hi:[1,0]
	v_pk_mul_f32 v[156:157], v[124:125], v[150:151] op_sel_hi:[1,0]
	v_pk_mul_f32 v[150:151], v[120:121], v[150:151] op_sel_hi:[1,0]
	v_mov_b32_e32 v160, v154
	v_mov_b32_e32 v161, v155
	v_cvt_pk_bf16_f32 v154, v156, v157
	v_cvt_pk_bf16_f32 v155, v160, v161
	v_cvt_pk_bf16_f32 v156, v150, v151
	v_cvt_pk_bf16_f32 v157, v158, v159
	global_store_dwordx4 v[136:137], v[154:157], off offset:256
	v_lshl_add_u64 v[150:151], v[152:153], 0, v[146:147]
	v_pk_mul_f32 v[146:147], v[102:103], v[148:149] op_sel_hi:[1,0]
	v_pk_mul_f32 v[154:155], v[100:101], v[148:149] op_sel_hi:[1,0]
	v_pk_mul_f32 v[156:157], v[98:99], v[148:149] op_sel_hi:[1,0]
	v_pk_mul_f32 v[158:159], v[96:97], v[148:149] op_sel_hi:[1,0]
	v_mov_b32_e32 v160, v156
	v_mov_b32_e32 v161, v157
	v_cvt_pk_bf16_f32 v154, v154, v155
	v_cvt_pk_bf16_f32 v155, v146, v147
	v_cvt_pk_bf16_f32 v156, v158, v159
	v_cvt_pk_bf16_f32 v157, v160, v161
	global_store_dwordx4 v[150:151], v[154:157], off
; __device__ __forceinline__ unsigned cvt_pk_bf16(float lo, float hi) { const f32x2 v = {lo, hi}; const bf16v2_t b = __builtin_convertvector(v, bf16v2_t); return __builtin_bit_cast(unsigned, b); }
; __device__ __forceinline__ float sigmoidf_(float x) { return __builtin_amdgcn_rcpf(1.0f + __builtin_amdgcn_exp2f(x * -1.44269504089f)); }
; __device__ __forceinline__ float siluf_(float x) { return x * __builtin_amdgcn_rcpf(1.0f + __builtin_amdgcn_exp2f(x * -1.44269504089f)); }
;     __device__ __forceinline__ void epi_proj(const f32x4 (&acc)[2][2][4][2], const pg8::Unit& u, int wr, int wc, int fr, int fq) const {
;     ...
;                         const int slot = u.pn >> 2;
;                         bf16_t* rowp = act + (size_t)slot * SLOT_EL + (size_t)r * 1024 + (colt & 1023);
; #pragma unroll
;                         for (int bj = 0; bj < 2; ++bj) {
;                             f32x4 v0 = acc[ai][bj][m][0] * rstd, v1 = acc[ai][bj][m][1] * rstd;
;                             if (slot < 2) {
;                                 f32x2 a = gelu_pk((f32x2){v0[0], v0[1]}), b = gelu_pk((f32x2){v0[2], v0[3]}), c = gelu_pk((f32x2){v1[0], v1[1]}), d = gelu_pk((f32x2){v1[2], v1[3]});
;                                 v0 = (f32x4){a.x, a.y, b.x, b.y}; v1 = (f32x4){c.x, c.y, d.x, d.y};
;                             } else if (slot == 5) {
; #pragma unroll
;                                 for (int j = 0; j < 4; ++j) { v0[j] = siluf_(v0[j]); v1[j] = siluf_(v1[j]); }
;                             } else if (slot >= 6) {
; #pragma unroll
;                                 for (int j = 0; j < 4; ++j) { v0[j] = sigmoidf_(v0[j]); v1[j] = sigmoidf_(v1[j]); }
;                             }
;                             u32x4 w; w.x = cvt_pk_bf16(v0[0], v0[1]); w.y = cvt_pk_bf16(v0[2], v0[3]); w.z = cvt_pk_bf16(v1[0], v1[1]); w.w = cvt_pk_bf16(v1[2], v1[3]);
;                             *(u32x4*)(rowp + bj * 128) = w;
;                             if (slot >= 2 && slot <= 4) {
;                                 const int ch = (slot - 2) * 1024 + (colt & 1023) + bj * 128;
;                                 if ((r & 63) >= 61) *(u32x4*)(halo + ((size_t)(r >> 6) * 3 + ((r & 63) - 61)) * 3072 + ch) = w;
	v_pk_mul_f32 v[146:147], v[110:111], v[148:149] op_sel_hi:[1,0]
	v_rsq_f32_e32 v128, v128
	v_pk_mul_f32 v[154:155], v[108:109], v[148:149] op_sel_hi:[1,0]
	v_pk_mul_f32 v[156:157], v[106:107], v[148:149] op_sel_hi:[1,0]
	v_pk_mul_f32 v[148:149], v[104:105], v[148:149] op_sel_hi:[1,0]
	v_mov_b32_e32 v158, v146
	v_mov_b32_e32 v159, v147
	v_cvt_pk_bf16_f32 v146, v154, v155
	v_cvt_pk_bf16_f32 v147, v158, v159
	v_cvt_pk_bf16_f32 v148, v148, v149
	v_cvt_pk_bf16_f32 v149, v156, v157
	global_store_dwordx4 v[150:151], v[146:149], off offset:256
	v_lshl_add_u64 v[150:151], v[152:153], 0, v[142:143]
	v_pk_mul_f32 v[142:143], v[86:87], v[144:145] op_sel_hi:[1,0]
	v_pk_mul_f32 v[146:147], v[84:85], v[144:145] op_sel_hi:[1,0]
	v_pk_mul_f32 v[148:149], v[82:83], v[144:145] op_sel_hi:[1,0]
	v_pk_mul_f32 v[154:155], v[80:81], v[144:145] op_sel_hi:[1,0]
	v_mov_b32_e32 v156, v148
	v_mov_b32_e32 v157, v149
	v_cvt_pk_bf16_f32 v146, v146, v147
	v_cvt_pk_bf16_f32 v147, v142, v143
	v_cvt_pk_bf16_f32 v148, v154, v155
	v_cvt_pk_bf16_f32 v149, v156, v157
	global_store_dwordx4 v[150:151], v[146:149], off
	v_pk_mul_f32 v[142:143], v[94:95], v[144:145] op_sel_hi:[1,0]
	s_mov_b64 s[0:1], 0x40000
	v_pk_mul_f32 v[146:147], v[92:93], v[144:145] op_sel_hi:[1,0]
	v_pk_mul_f32 v[148:149], v[90:91], v[144:145] op_sel_hi:[1,0]
	v_pk_mul_f32 v[144:145], v[88:89], v[144:145] op_sel_hi:[1,0]
	v_mov_b32_e32 v154, v142
	v_mov_b32_e32 v155, v143
	v_cvt_pk_bf16_f32 v142, v146, v147
	v_cvt_pk_bf16_f32 v143, v154, v155
	v_cvt_pk_bf16_f32 v144, v144, v145
	v_cvt_pk_bf16_f32 v145, v148, v149
	global_store_dwordx4 v[150:151], v[142:145], off offset:256
	v_pk_mul_f32 v[146:147], v[66:67], v[138:139] op_sel_hi:[1,0]
	v_pk_mul_f32 v[148:149], v[64:65], v[138:139] op_sel_hi:[1,0]
	v_lshl_add_u64 v[144:145], v[152:153], 0, v[140:141]
	v_pk_mul_f32 v[140:141], v[70:71], v[138:139] op_sel_hi:[1,0]
	v_pk_mul_f32 v[142:143], v[68:69], v[138:139] op_sel_hi:[1,0]
	v_mov_b32_e32 v150, v140
	v_mov_b32_e32 v151, v141
	v_cvt_pk_bf16_f32 v140, v142, v143
	v_cvt_pk_bf16_f32 v141, v150, v151
	v_cvt_pk_bf16_f32 v142, v148, v149
	v_cvt_pk_bf16_f32 v143, v146, v147
	global_store_dwordx4 v[144:145], v[140:143], off
	s_and_saveexec_b64 s[100:101], s[36:37]
	global_store_dwordx4 v[166:167], v[140:143], off
	s_mov_b64 exec, s[100:101]
	v_pk_mul_f32 v[146:147], v[74:75], v[138:139] op_sel_hi:[1,0]
	v_mul_f32_e32 v129, 0x45800000, v128
	v_pk_mul_f32 v[140:141], v[78:79], v[138:139] op_sel_hi:[1,0]
	v_pk_mul_f32 v[142:143], v[76:77], v[138:139] op_sel_hi:[1,0]
	v_pk_mul_f32 v[138:139], v[72:73], v[138:139] op_sel_hi:[1,0]
	v_mov_b32_e32 v148, v138
	v_mov_b32_e32 v149, v139
	v_mov_b32_e32 v138, v140
	v_mov_b32_e32 v140, v146
	v_mov_b32_e32 v139, v141
	v_mov_b32_e32 v141, v147
	v_mov_b32_e32 v150, v138
	v_mov_b32_e32 v151, v139
	v_mov_b32_e32 v146, v140
	v_mov_b32_e32 v147, v141
	v_cvt_pk_bf16_f32 v138, v142, v143
	v_cvt_pk_bf16_f32 v139, v150, v151
	v_cvt_pk_bf16_f32 v140, v148, v149
	v_cvt_pk_bf16_f32 v141, v146, v147
	global_store_dwordx4 v[144:145], v[138:141], off offset:256
	s_and_saveexec_b64 s[100:101], s[36:37]
	global_store_dwordx4 v[166:167], v[138:141], off offset:256
	s_mov_b64 exec, s[100:101]
	v_pk_mul_f32 v[144:145], v[50:51], v[134:135] op_sel_hi:[1,0]
	v_pk_mul_f32 v[146:147], v[48:49], v[134:135] op_sel_hi:[1,0]
	v_pk_mul_f32 v[140:141], v[52:53], v[134:135] op_sel_hi:[1,0]
	v_pk_mul_f32 v[138:139], v[54:55], v[134:135] op_sel_hi:[1,0]
	v_lshl_add_u64 v[142:143], v[136:137], 0, s[0:1]
	s_mov_b32 s0, 0x40000
	v_cndmask_b32_e32 v128, v128, v129, vcc
	v_mov_b32_e32 v148, v138
	v_mov_b32_e32 v149, v139
	v_cvt_pk_bf16_f32 v138, v140, v141
	v_cvt_pk_bf16_f32 v141, v144, v145
	v_add_co_u32_e32 v144, vcc, s0, v136
	v_cvt_pk_bf16_f32 v139, v148, v149
	v_cvt_pk_bf16_f32 v140, v146, v147
	v_addc_co_u32_e32 v145, vcc, 0, v137, vcc
	global_store_dwordx4 v[144:145], v[138:141], off
	v_pk_mul_f32 v[144:145], v[58:59], v[134:135] op_sel_hi:[1,0]
	s_mov_b64 s[0:1], 0x48000
	v_pk_mul_f32 v[138:139], v[62:63], v[134:135] op_sel_hi:[1,0]
	v_pk_mul_f32 v[140:141], v[60:61], v[134:135] op_sel_hi:[1,0]
	v_pk_mul_f32 v[134:135], v[56:57], v[134:135] op_sel_hi:[1,0]
	v_mov_b32_e32 v146, v138
	v_mov_b32_e32 v147, v139
	v_cvt_pk_bf16_f32 v138, v140, v141
	v_cvt_pk_bf16_f32 v139, v146, v147
	v_cvt_pk_bf16_f32 v140, v134, v135
	v_cvt_pk_bf16_f32 v141, v144, v145
	global_store_dwordx4 v[142:143], v[138:141], off offset:256
	v_pk_mul_f32 v[134:135], v[38:39], v[132:133] op_sel_hi:[1,0]
	v_pk_mul_f32 v[144:145], v[32:33], v[132:133] op_sel_hi:[1,0]
	v_pk_mul_f32 v[138:139], v[36:37], v[132:133] op_sel_hi:[1,0]
;     __device__ __forceinline__ void epi_proj(const f32x4 (&acc)[2][2][4][2], const pg8::Unit& u, int wr, int wc, int fr, int fq) const {
;     ...
;                     if (u.pn == 32) {
;     ...
;                         const int slot = u.pn >> 2;
;                         bf16_t* rowp = act + (size_t)slot * SLOT_EL + (size_t)r * 1024 + (colt & 1023);
; #pragma unroll
;                         for (int bj = 0; bj < 2; ++bj) {
;                             f32x4 v0 = acc[ai][bj][m][0] * rstd, v1 = acc[ai][bj][m][1] * rstd;
;                             if (slot < 2) {
;                                 f32x2 a = gelu_pk((f32x2){v0[0], v0[1]}), b = gelu_pk((f32x2){v0[2], v0[3]}), c = gelu_pk((f32x2){v1[0], v1[1]}), d = gelu_pk((f32x2){v1[2], v1[3]});
;                                 v0 = (f32x4){a.x, a.y, b.x, b.y}; v1 = (f32x4){c.x, c.y, d.x, d.y};
;                             } else if (slot == 5) {
; #pragma unroll
;                                 for (int j = 0; j < 4; ++j) { v0[j] = siluf_(v0[j]); v1[j] = siluf_(v1[j]); }
;                             } else if (slot >= 6) {
; #pragma unroll
;                                 for (int j = 0; j < 4; ++j) { v0[j] = sigmoidf_(v0[j]); v1[j] = sigmoidf_(v1[j]); }
;                             }
;                             u32x4 w; w.x = cvt_pk_bf16(v0[0], v0[1]); w.y = cvt_pk_bf16(v0[2], v0[3]); w.z = cvt_pk_bf16(v1[0], v1[1]); w.w = cvt_pk_bf16(v1[2], v1[3]);
;                             *(u32x4*)(rowp + bj * 128) = w;
;                             if (slot >= 2 && slot <= 4) {
;                                 const int ch = (slot - 2) * 1024 + (colt & 1023) + bj * 128;
;                                 if ((r & 63) >= 61) *(u32x4*)(halo + ((size_t)(r >> 6) * 3 + ((r & 63) - 61)) * 3072 + ch) = w;
;                                 float* cdst = nullptr;
;                                 if (r < 32768) { if ((r & 4095) >= 4093) cdst = out + OCP + (((size_t)l * 16 + g * 8 + (r >> 12)) * 3 + ((r & 4095) - 4093)) * 3072 + ch; }
;                                 else if (g == 0 && r < 32896) { const int rr = r - 32768; if ((rr & 15) >= 13) cdst = out + OCS + (((size_t)l * 8 + (rr >> 4)) * 3 + ((rr & 15) - 13)) * 3072 + ch; }
;                                 if (cdst) { *(f32x4*)cdst = v0; *(f32x4*)(cdst + 4) = v1; }
;                             }
	v_pk_mul_f32 v[140:141], v[34:35], v[132:133] op_sel_hi:[1,0]
	v_lshl_add_u64 v[142:143], v[136:137], 0, s[0:1]
	s_mov_b32 s0, 0x48000
	v_mov_b32_e32 v146, v140
	v_mov_b32_e32 v147, v141
	v_cvt_pk_bf16_f32 v138, v138, v139
	v_cvt_pk_bf16_f32 v139, v134, v135
	v_add_co_u32_e32 v134, vcc, s0, v136
	v_cvt_pk_bf16_f32 v140, v144, v145
	v_cvt_pk_bf16_f32 v141, v146, v147
	v_addc_co_u32_e32 v135, vcc, 0, v137, vcc
	global_store_dwordx4 v[134:135], v[138:141], off
	v_pk_mul_f32 v[134:135], v[46:47], v[132:133] op_sel_hi:[1,0]
	s_mov_b64 s[0:1], 0x50000
	v_pk_mul_f32 v[138:139], v[44:45], v[132:133] op_sel_hi:[1,0]
	v_pk_mul_f32 v[140:141], v[42:43], v[132:133] op_sel_hi:[1,0]
	v_pk_mul_f32 v[132:133], v[40:41], v[132:133] op_sel_hi:[1,0]
	v_mov_b32_e32 v144, v132
	v_mov_b32_e32 v145, v133
	v_mov_b32_e32 v132, v134
	v_mov_b32_e32 v134, v140
	v_mov_b32_e32 v133, v135
	v_mov_b32_e32 v135, v141
	v_mov_b32_e32 v146, v132
	v_mov_b32_e32 v147, v133
	v_mov_b32_e32 v140, v134
	v_mov_b32_e32 v141, v135
	v_cvt_pk_bf16_f32 v132, v138, v139
	v_cvt_pk_bf16_f32 v133, v146, v147
	v_cvt_pk_bf16_f32 v134, v144, v145
	v_cvt_pk_bf16_f32 v135, v140, v141
	global_store_dwordx4 v[142:143], v[132:135], off offset:256
	v_pk_mul_f32 v[140:141], v[18:19], v[130:131] op_sel_hi:[1,0]
	v_pk_mul_f32 v[142:143], v[16:17], v[130:131] op_sel_hi:[1,0]
	v_pk_mul_f32 v[134:135], v[20:21], v[130:131] op_sel_hi:[1,0]
	v_pk_mul_f32 v[132:133], v[22:23], v[130:131] op_sel_hi:[1,0]
	v_lshl_add_u64 v[138:139], v[136:137], 0, s[0:1]
	s_mov_b32 s0, 0x50000
	v_mov_b32_e32 v144, v132
	v_mov_b32_e32 v145, v133
	v_cvt_pk_bf16_f32 v132, v134, v135
	v_cvt_pk_bf16_f32 v135, v140, v141
	v_add_co_u32_e32 v140, vcc, s0, v136
	v_cvt_pk_bf16_f32 v133, v144, v145
	v_cvt_pk_bf16_f32 v134, v142, v143
	v_addc_co_u32_e32 v141, vcc, 0, v137, vcc
	global_store_dwordx4 v[140:141], v[132:135], off
	v_pk_mul_f32 v[140:141], v[26:27], v[130:131] op_sel_hi:[1,0]
	s_mov_b64 s[0:1], 0x58000
	v_pk_mul_f32 v[132:133], v[30:31], v[130:131] op_sel_hi:[1,0]
	v_pk_mul_f32 v[134:135], v[28:29], v[130:131] op_sel_hi:[1,0]
	v_pk_mul_f32 v[130:131], v[24:25], v[130:131] op_sel_hi:[1,0]
	v_mov_b32_e32 v142, v130
	v_mov_b32_e32 v143, v131
	v_mov_b32_e32 v130, v132
	v_mov_b32_e32 v132, v140
	v_mov_b32_e32 v131, v133
	v_mov_b32_e32 v133, v141
	v_mov_b32_e32 v144, v130
	v_mov_b32_e32 v145, v131
	v_mov_b32_e32 v140, v132
	v_mov_b32_e32 v141, v133
	v_cvt_pk_bf16_f32 v130, v134, v135
	v_cvt_pk_bf16_f32 v131, v144, v145
	v_cvt_pk_bf16_f32 v132, v142, v143
	v_cvt_pk_bf16_f32 v133, v140, v141
	global_store_dwordx4 v[138:139], v[130:133], off offset:256
	v_pk_mul_f32 v[138:139], v[2:3], v[128:129] op_sel_hi:[1,0]
	v_pk_mul_f32 v[140:141], v[0:1], v[128:129] op_sel_hi:[1,0]
	v_pk_mul_f32 v[130:131], v[6:7], v[128:129] op_sel_hi:[1,0]
	v_pk_mul_f32 v[132:133], v[4:5], v[128:129] op_sel_hi:[1,0]
	v_lshl_add_u64 v[134:135], v[136:137], 0, s[0:1]
	s_mov_b32 s0, 0x58000
	v_mov_b32_e32 v142, v130
	v_mov_b32_e32 v143, v131
	v_add_co_u32_e32 v136, vcc, s0, v136
	v_cvt_pk_bf16_f32 v130, v132, v133
	v_cvt_pk_bf16_f32 v131, v142, v143
	v_cvt_pk_bf16_f32 v132, v140, v141
	v_cvt_pk_bf16_f32 v133, v138, v139
	v_addc_co_u32_e32 v137, vcc, 0, v137, vcc
	global_store_dwordx4 v[136:137], v[130:133], off
	s_and_saveexec_b64 s[100:101], s[36:37]
	global_store_dwordx4 v[168:169], v[130:133], off
	s_mov_b64 exec, s[100:101]
	v_pk_mul_f32 v[136:137], v[10:11], v[128:129] op_sel_hi:[1,0]
	s_nop 0
	v_pk_mul_f32 v[130:131], v[14:15], v[128:129] op_sel_hi:[1,0]
	v_pk_mul_f32 v[132:133], v[12:13], v[128:129] op_sel_hi:[1,0]
	v_pk_mul_f32 v[128:129], v[8:9], v[128:129] op_sel_hi:[1,0]
	v_mov_b32_e32 v138, v128
	v_mov_b32_e32 v139, v129
	v_mov_b32_e32 v128, v130
	v_mov_b32_e32 v130, v136
	v_mov_b32_e32 v129, v131
	v_mov_b32_e32 v131, v137
	v_mov_b32_e32 v140, v128
	v_mov_b32_e32 v141, v129
	v_mov_b32_e32 v136, v130
	v_mov_b32_e32 v137, v131
	v_cvt_pk_bf16_f32 v128, v132, v133
	v_cvt_pk_bf16_f32 v129, v140, v141
	v_cvt_pk_bf16_f32 v130, v138, v139
	v_cvt_pk_bf16_f32 v131, v136, v137
	global_store_dwordx4 v[134:135], v[128:131], off offset:256
	s_and_saveexec_b64 s[100:101], s[36:37]
	global_store_dwordx4 v[168:169], v[128:131], off offset:256
	s_mov_b64 exec, s[100:101]
	s_branch .LBB0_701
.LBB0_1031:
	s_cmp_eq_u32 s88, 32
	s_cbranch_scc1 .Lproj_orig
	s_lshr_b32 s100, s88, 2
	s_cmp_ge_u32 s100, 6
	s_cbranch_scc1 .Lepi_sig
	s_cmp_eq_u32 s100, 5
	s_cbranch_scc1 .Lepi_silu
	s_cmp_lt_u32 s100, 2
	s_cbranch_scc1 .Lproj_orig
	s_cmp_gt_u32 s100, 4
	s_cbranch_scc1 .Lproj_orig
	s_and_b32 s101, s13, 15
	s_cmp_eq_u32 s101, 15
	s_cbranch_scc1 .Lproj_orig
	s_cmp_eq_u32 s13, 0x80
	s_cbranch_scc0 .Lepi_plain
